# on top of the segment-head version: B fragment LDS reads through one base VGPR + immediate offsets (no VALU address add behind the barrier)
# speedup vs baseline: 1.0079x; 1.0079x over previous
.LBB0_318:
	ds_read_b128 v[146:149], v194
	ds_read_b128 v[150:153], v194 offset:1024
	ds_read_b128 v[154:157], v194 offset:2048
	ds_read_b128 v[158:161], v194 offset:3072
	ds_read_b128 v[130:133], v194 offset:16384
	ds_read_b128 v[134:137], v194 offset:17408
	ds_read_b128 v[138:141], v194 offset:18432
	ds_read_b128 v[142:145], v194 offset:19456
	s_add_u32 s42, s93, s9
	s_addc_u32 s43, s94, 0
	s_add_u32 s42, s42, 0xffffff80
	s_addc_u32 s43, s43, -1
	s_mov_b32 s74, m0
	s_mov_b32 m0, s65
	s_nop 0
	global_load_lds_dwordx4 v245, s[42:43]
	s_mov_b32 m0, s74
	s_nop 0
	s_mov_b32 s74, m0
	s_mov_b32 m0, s66
	s_nop 0
	global_load_lds_dwordx4 v247, s[42:43]
	s_mov_b32 m0, s74
	s_cmp_eq_u32 s57, s3
	s_cselect_b32 s73, s55, s94
	s_cselect_b32 s72, s54, s93
	s_cselect_b32 s77, s63, s92
	s_cselect_b32 s76, s62, s8
	s_waitcnt lgkmcnt(0)
	ds_read_b128 v[162:165], v252
	ds_read_b128 v[166:169], v252 offset:1024
	ds_read_b128 v[170:173], v252 offset:2048
	ds_read_b128 v[174:177], v252 offset:3072
	ds_read_b128 v[178:181], v252 offset:4096
	ds_read_b128 v[182:185], v252 offset:5120
	ds_read_b128 v[186:189], v252 offset:6144
	ds_read_b128 v[190:193], v252 offset:7168
	s_waitcnt vmcnt(8)
	s_waitcnt lgkmcnt(0)
	s_setprio 1
	s_barrier
	v_mfma_f32_16x16x32_bf16 v[124:127], v[146:149], v[162:165], v[124:127]
	v_mfma_f32_16x16x32_bf16 v[120:123], v[154:157], v[162:165], v[120:123]
	v_mfma_f32_16x16x32_bf16 v[108:111], v[146:149], v[170:173], v[108:111]
	v_mfma_f32_16x16x32_bf16 v[104:107], v[154:157], v[170:173], v[104:107]
	v_mfma_f32_16x16x32_bf16 v[92:95], v[146:149], v[178:181], v[92:95]
	v_mfma_f32_16x16x32_bf16 v[88:91], v[154:157], v[178:181], v[88:91]
	v_mfma_f32_16x16x32_bf16 v[76:79], v[146:149], v[186:189], v[76:79]
	v_mfma_f32_16x16x32_bf16 v[72:75], v[154:157], v[186:189], v[72:75]
	v_mfma_f32_16x16x32_bf16 v[124:127], v[150:153], v[166:169], v[124:127]
	v_mfma_f32_16x16x32_bf16 v[120:123], v[158:161], v[166:169], v[120:123]
	v_mfma_f32_16x16x32_bf16 v[108:111], v[150:153], v[174:177], v[108:111]
	v_mfma_f32_16x16x32_bf16 v[104:107], v[158:161], v[174:177], v[104:107]
	v_mfma_f32_16x16x32_bf16 v[92:95], v[150:153], v[182:185], v[92:95]
	v_mfma_f32_16x16x32_bf16 v[88:91], v[158:161], v[182:185], v[88:91]
	v_mfma_f32_16x16x32_bf16 v[76:79], v[150:153], v[190:193], v[76:79]
	v_mfma_f32_16x16x32_bf16 v[72:75], v[158:161], v[190:193], v[72:75]
	s_setprio 0
	s_setprio 1
	v_mfma_f32_16x16x32_bf16 v[116:119], v[130:133], v[162:165], v[116:119]
	v_mfma_f32_16x16x32_bf16 v[112:115], v[138:141], v[162:165], v[112:115]
	v_mfma_f32_16x16x32_bf16 v[100:103], v[130:133], v[170:173], v[100:103]
	v_mfma_f32_16x16x32_bf16 v[96:99], v[138:141], v[170:173], v[96:99]
	v_mfma_f32_16x16x32_bf16 v[84:87], v[130:133], v[178:181], v[84:87]
	v_mfma_f32_16x16x32_bf16 v[80:83], v[138:141], v[178:181], v[80:83]
	v_mfma_f32_16x16x32_bf16 v[68:71], v[130:133], v[186:189], v[68:71]
	v_mfma_f32_16x16x32_bf16 v[64:67], v[138:141], v[186:189], v[64:67]
	v_mfma_f32_16x16x32_bf16 v[116:119], v[134:137], v[166:169], v[116:119]
	v_mfma_f32_16x16x32_bf16 v[112:115], v[142:145], v[166:169], v[112:115]
	v_mfma_f32_16x16x32_bf16 v[100:103], v[134:137], v[174:177], v[100:103]
	v_mfma_f32_16x16x32_bf16 v[96:99], v[142:145], v[174:177], v[96:99]
	v_mfma_f32_16x16x32_bf16 v[84:87], v[134:137], v[182:185], v[84:87]
	v_mfma_f32_16x16x32_bf16 v[80:83], v[142:145], v[182:185], v[80:83]
	v_mfma_f32_16x16x32_bf16 v[68:71], v[134:137], v[190:193], v[68:71]
	v_mfma_f32_16x16x32_bf16 v[64:67], v[142:145], v[190:193], v[64:67]
	s_setprio 0
	s_barrier
	s_mov_b32 s42, m0
	s_mov_b32 m0, s14
	s_nop 0
	global_load_lds_dwordx4 v246, s[76:77]
	s_mov_b32 m0, s42
	s_add_u32 s74, s76, s9
	s_mov_b32 s42, m0
	s_mov_b32 m0, s15
	s_nop 0
	global_load_lds_dwordx4 v248, s[76:77]
	s_mov_b32 m0, s42
	s_addc_u32 s75, s77, 0
	s_mov_b32 s42, m0
	s_mov_b32 m0, s16
	s_nop 0
	global_load_lds_dwordx4 v246, s[74:75]
	s_mov_b32 m0, s42
	v_cndmask_b32_e64 v128, 0, 1, s[68:69]
	s_mov_b32 s42, m0
	s_mov_b32 m0, s17
	s_nop 0
	global_load_lds_dwordx4 v248, s[74:75]
	s_mov_b32 m0, s42
	s_andn2_b64 vcc, exec, s[68:69]
	s_mov_b32 s42, m0
	s_mov_b32 m0, s11
	s_nop 0
	global_load_lds_dwordx4 v245, s[72:73]
	s_mov_b32 m0, s42
	s_nop 0
	s_mov_b32 s42, m0
	s_mov_b32 m0, s19
	s_nop 0
	global_load_lds_dwordx4 v247, s[72:73]
	s_mov_b32 m0, s42
	ds_read_b128 v[186:189], v252 offset:16384
	ds_read_b128 v[190:193], v252 offset:17408
	ds_read_b128 v[178:181], v252 offset:18432
	ds_read_b128 v[182:185], v252 offset:19456
	ds_read_b128 v[170:173], v252 offset:20480
	ds_read_b128 v[174:177], v252 offset:21504
	ds_read_b128 v[162:165], v252 offset:22528
	ds_read_b128 v[166:169], v252 offset:23552
	v_cmp_ne_u32_e64 s[42:43], 1, v128
	s_waitcnt vmcnt(8)
	s_waitcnt lgkmcnt(0)
	s_barrier
	s_cbranch_vccnz .LBB0_320
	s_setprio 1
	v_mfma_f32_16x16x32_bf16 v[60:63], v[146:149], v[186:189], v[60:63]
	v_mfma_f32_16x16x32_bf16 v[56:59], v[154:157], v[186:189], v[56:59]
	v_mfma_f32_16x16x32_bf16 v[44:47], v[146:149], v[178:181], v[44:47]
	v_mfma_f32_16x16x32_bf16 v[40:43], v[154:157], v[178:181], v[40:43]
	v_mfma_f32_16x16x32_bf16 v[28:31], v[146:149], v[170:173], v[28:31]
	v_mfma_f32_16x16x32_bf16 v[24:27], v[154:157], v[170:173], v[24:27]
	v_mfma_f32_16x16x32_bf16 v[12:15], v[146:149], v[162:165], v[12:15]
	v_mfma_f32_16x16x32_bf16 v[8:11], v[154:157], v[162:165], v[8:11]
	v_mfma_f32_16x16x32_bf16 v[60:63], v[150:153], v[190:193], v[60:63]
	v_mfma_f32_16x16x32_bf16 v[56:59], v[158:161], v[190:193], v[56:59]
	v_mfma_f32_16x16x32_bf16 v[44:47], v[150:153], v[182:185], v[44:47]
	v_mfma_f32_16x16x32_bf16 v[40:43], v[158:161], v[182:185], v[40:43]
	v_mfma_f32_16x16x32_bf16 v[28:31], v[150:153], v[174:177], v[28:31]
	v_mfma_f32_16x16x32_bf16 v[24:27], v[158:161], v[174:177], v[24:27]
	v_mfma_f32_16x16x32_bf16 v[12:15], v[150:153], v[166:169], v[12:15]
	v_mfma_f32_16x16x32_bf16 v[8:11], v[158:161], v[166:169], v[8:11]
	s_setprio 0
	s_setprio 1
	v_mfma_f32_16x16x32_bf16 v[52:55], v[130:133], v[186:189], v[52:55]
	v_mfma_f32_16x16x32_bf16 v[48:51], v[138:141], v[186:189], v[48:51]
	v_mfma_f32_16x16x32_bf16 v[36:39], v[130:133], v[178:181], v[36:39]
	v_mfma_f32_16x16x32_bf16 v[32:35], v[138:141], v[178:181], v[32:35]
	v_mfma_f32_16x16x32_bf16 v[20:23], v[130:133], v[170:173], v[20:23]
	v_mfma_f32_16x16x32_bf16 v[16:19], v[138:141], v[170:173], v[16:19]
	v_mfma_f32_16x16x32_bf16 v[4:7], v[130:133], v[162:165], v[4:7]
	v_mfma_f32_16x16x32_bf16 v[0:3], v[138:141], v[162:165], v[0:3]
	v_mfma_f32_16x16x32_bf16 v[52:55], v[134:137], v[190:193], v[52:55]
	v_mfma_f32_16x16x32_bf16 v[48:51], v[142:145], v[190:193], v[48:51]
	v_mfma_f32_16x16x32_bf16 v[36:39], v[134:137], v[182:185], v[36:39]
	v_mfma_f32_16x16x32_bf16 v[32:35], v[142:145], v[182:185], v[32:35]
	v_mfma_f32_16x16x32_bf16 v[20:23], v[134:137], v[174:177], v[20:23]
	v_mfma_f32_16x16x32_bf16 v[16:19], v[142:145], v[174:177], v[16:19]
	v_mfma_f32_16x16x32_bf16 v[4:7], v[134:137], v[166:169], v[4:7]
	v_mfma_f32_16x16x32_bf16 v[0:3], v[142:145], v[166:169], v[0:3]
	s_setprio 0
.LBB0_320:
	s_add_u32 s80, s72, 0x80
	s_addc_u32 s81, s73, 0
	s_add_u32 s76, s76, 0x80
	s_addc_u32 s77, s77, 0
	s_barrier
	ds_read_b128 v[146:149], v194 offset:32768
	ds_read_b128 v[150:153], v194 offset:33792
	ds_read_b128 v[154:157], v194 offset:34816
	ds_read_b128 v[158:161], v194 offset:35840
	ds_read_b128 v[130:133], v194 offset:49152
	ds_read_b128 v[134:137], v194 offset:50176
	ds_read_b128 v[138:141], v194 offset:51200
	ds_read_b128 v[142:145], v194 offset:52224
	s_add_u32 s72, s72, s9
	s_addc_u32 s73, s73, 0
	s_mov_b32 s95, m0
	s_mov_b32 m0, s20
	s_nop 0
	global_load_lds_dwordx4 v245, s[72:73]
	s_mov_b32 m0, s95
	s_nop 0
	s_mov_b32 s95, m0
	s_mov_b32 m0, s21
	s_nop 0
	global_load_lds_dwordx4 v247, s[72:73]
	s_mov_b32 m0, s95
	s_waitcnt lgkmcnt(0)
	ds_read_b128 v[162:165], v252 offset:32768
	ds_read_b128 v[166:169], v252 offset:33792
	ds_read_b128 v[170:173], v252 offset:34816
	ds_read_b128 v[174:177], v252 offset:35840
	ds_read_b128 v[178:181], v252 offset:36864
	ds_read_b128 v[182:185], v252 offset:37888
	ds_read_b128 v[186:189], v252 offset:38912
	ds_read_b128 v[190:193], v252 offset:39936
	s_waitcnt vmcnt(8)
	s_waitcnt lgkmcnt(0)
	s_setprio 1
	s_barrier
	v_mfma_f32_16x16x32_bf16 v[124:127], v[146:149], v[162:165], v[124:127]
	v_mfma_f32_16x16x32_bf16 v[120:123], v[154:157], v[162:165], v[120:123]
	v_mfma_f32_16x16x32_bf16 v[108:111], v[146:149], v[170:173], v[108:111]
	v_mfma_f32_16x16x32_bf16 v[104:107], v[154:157], v[170:173], v[104:107]
	v_mfma_f32_16x16x32_bf16 v[92:95], v[146:149], v[178:181], v[92:95]
	v_mfma_f32_16x16x32_bf16 v[88:91], v[154:157], v[178:181], v[88:91]
	v_mfma_f32_16x16x32_bf16 v[76:79], v[146:149], v[186:189], v[76:79]
	v_mfma_f32_16x16x32_bf16 v[72:75], v[154:157], v[186:189], v[72:75]
	v_mfma_f32_16x16x32_bf16 v[124:127], v[150:153], v[166:169], v[124:127]
	v_mfma_f32_16x16x32_bf16 v[120:123], v[158:161], v[166:169], v[120:123]
	v_mfma_f32_16x16x32_bf16 v[108:111], v[150:153], v[174:177], v[108:111]
	v_mfma_f32_16x16x32_bf16 v[104:107], v[158:161], v[174:177], v[104:107]
	v_mfma_f32_16x16x32_bf16 v[92:95], v[150:153], v[182:185], v[92:95]
	v_mfma_f32_16x16x32_bf16 v[88:91], v[158:161], v[182:185], v[88:91]
	v_mfma_f32_16x16x32_bf16 v[76:79], v[150:153], v[190:193], v[76:79]
	v_mfma_f32_16x16x32_bf16 v[72:75], v[158:161], v[190:193], v[72:75]
	s_setprio 0
	s_setprio 1
	v_mfma_f32_16x16x32_bf16 v[116:119], v[130:133], v[162:165], v[116:119]
	v_mfma_f32_16x16x32_bf16 v[112:115], v[138:141], v[162:165], v[112:115]
	v_mfma_f32_16x16x32_bf16 v[100:103], v[130:133], v[170:173], v[100:103]
	v_mfma_f32_16x16x32_bf16 v[96:99], v[138:141], v[170:173], v[96:99]
	v_mfma_f32_16x16x32_bf16 v[84:87], v[130:133], v[178:181], v[84:87]
	v_mfma_f32_16x16x32_bf16 v[80:83], v[138:141], v[178:181], v[80:83]
	v_mfma_f32_16x16x32_bf16 v[68:71], v[130:133], v[186:189], v[68:71]
	v_mfma_f32_16x16x32_bf16 v[64:67], v[138:141], v[186:189], v[64:67]
	v_mfma_f32_16x16x32_bf16 v[116:119], v[134:137], v[166:169], v[116:119]
	v_mfma_f32_16x16x32_bf16 v[112:115], v[142:145], v[166:169], v[112:115]
	v_mfma_f32_16x16x32_bf16 v[100:103], v[134:137], v[174:177], v[100:103]
	v_mfma_f32_16x16x32_bf16 v[96:99], v[142:145], v[174:177], v[96:99]
	v_mfma_f32_16x16x32_bf16 v[84:87], v[134:137], v[182:185], v[84:87]
	v_mfma_f32_16x16x32_bf16 v[80:83], v[142:145], v[182:185], v[80:83]
	v_mfma_f32_16x16x32_bf16 v[68:71], v[134:137], v[190:193], v[68:71]
	v_mfma_f32_16x16x32_bf16 v[64:67], v[142:145], v[190:193], v[64:67]
	s_setprio 0
	s_barrier
	s_mov_b32 s72, m0
	s_mov_b32 m0, s23
	s_nop 0
	global_load_lds_dwordx4 v246, s[76:77]
	s_mov_b32 m0, s72
	s_nop 0
	s_mov_b32 s72, m0
	s_mov_b32 m0, s30
	s_nop 0
	global_load_lds_dwordx4 v248, s[76:77]
	s_mov_b32 m0, s72
	s_add_u32 s72, s74, 0x80
	s_addc_u32 s73, s75, 0
	s_mov_b32 s74, m0
	s_mov_b32 m0, s52
	s_nop 0
	global_load_lds_dwordx4 v246, s[72:73]
	s_mov_b32 m0, s74
	s_and_b64 vcc, exec, s[42:43]
	s_mov_b32 s74, m0
	s_mov_b32 m0, s53
	s_nop 0
	global_load_lds_dwordx4 v248, s[72:73]
	s_mov_b32 m0, s74
	s_mov_b32 s72, m0
	s_mov_b32 m0, s47
	s_nop 0
	global_load_lds_dwordx4 v245, s[80:81]
	s_mov_b32 m0, s72
	s_nop 0
	s_mov_b32 s72, m0
	s_mov_b32 m0, s50
	s_nop 0
	global_load_lds_dwordx4 v247, s[80:81]
	s_mov_b32 m0, s72
	ds_read_b128 v[186:189], v252 offset:49152
	ds_read_b128 v[190:193], v252 offset:50176
	ds_read_b128 v[178:181], v252 offset:51200
	ds_read_b128 v[182:185], v252 offset:52224
	ds_read_b128 v[170:173], v252 offset:53248
	ds_read_b128 v[174:177], v252 offset:54272
	ds_read_b128 v[162:165], v252 offset:55296
	ds_read_b128 v[166:169], v252 offset:56320
	s_waitcnt vmcnt(8)
	s_waitcnt lgkmcnt(0)
	s_barrier
	s_cbranch_vccnz .LBB0_317
	s_setprio 1
	v_mfma_f32_16x16x32_bf16 v[60:63], v[146:149], v[186:189], v[60:63]
	v_mfma_f32_16x16x32_bf16 v[56:59], v[154:157], v[186:189], v[56:59]
	v_mfma_f32_16x16x32_bf16 v[44:47], v[146:149], v[178:181], v[44:47]
	v_mfma_f32_16x16x32_bf16 v[40:43], v[154:157], v[178:181], v[40:43]
	v_mfma_f32_16x16x32_bf16 v[28:31], v[146:149], v[170:173], v[28:31]
	v_mfma_f32_16x16x32_bf16 v[24:27], v[154:157], v[170:173], v[24:27]
	v_mfma_f32_16x16x32_bf16 v[12:15], v[146:149], v[162:165], v[12:15]
	v_mfma_f32_16x16x32_bf16 v[8:11], v[154:157], v[162:165], v[8:11]
	v_mfma_f32_16x16x32_bf16 v[60:63], v[150:153], v[190:193], v[60:63]
	v_mfma_f32_16x16x32_bf16 v[56:59], v[158:161], v[190:193], v[56:59]
	v_mfma_f32_16x16x32_bf16 v[44:47], v[150:153], v[182:185], v[44:47]
	v_mfma_f32_16x16x32_bf16 v[40:43], v[158:161], v[182:185], v[40:43]
	v_mfma_f32_16x16x32_bf16 v[28:31], v[150:153], v[174:177], v[28:31]
	v_mfma_f32_16x16x32_bf16 v[24:27], v[158:161], v[174:177], v[24:27]
	v_mfma_f32_16x16x32_bf16 v[12:15], v[150:153], v[166:169], v[12:15]
	v_mfma_f32_16x16x32_bf16 v[8:11], v[158:161], v[166:169], v[8:11]
	s_setprio 0
	s_setprio 1
	v_mfma_f32_16x16x32_bf16 v[52:55], v[130:133], v[186:189], v[52:55]
	v_mfma_f32_16x16x32_bf16 v[48:51], v[138:141], v[186:189], v[48:51]
	v_mfma_f32_16x16x32_bf16 v[36:39], v[130:133], v[178:181], v[36:39]
	v_mfma_f32_16x16x32_bf16 v[32:35], v[138:141], v[178:181], v[32:35]
	v_mfma_f32_16x16x32_bf16 v[20:23], v[130:133], v[170:173], v[20:23]
	v_mfma_f32_16x16x32_bf16 v[16:19], v[138:141], v[170:173], v[16:19]
	v_mfma_f32_16x16x32_bf16 v[4:7], v[130:133], v[162:165], v[4:7]
	v_mfma_f32_16x16x32_bf16 v[0:3], v[138:141], v[162:165], v[0:3]
	v_mfma_f32_16x16x32_bf16 v[52:55], v[134:137], v[190:193], v[52:55]
	v_mfma_f32_16x16x32_bf16 v[48:51], v[142:145], v[190:193], v[48:51]
	v_mfma_f32_16x16x32_bf16 v[36:39], v[134:137], v[182:185], v[36:39]
	v_mfma_f32_16x16x32_bf16 v[32:35], v[142:145], v[182:185], v[32:35]
	v_mfma_f32_16x16x32_bf16 v[20:23], v[134:137], v[174:177], v[20:23]
	v_mfma_f32_16x16x32_bf16 v[16:19], v[142:145], v[174:177], v[16:19]
	v_mfma_f32_16x16x32_bf16 v[4:7], v[134:137], v[166:169], v[4:7]
	v_mfma_f32_16x16x32_bf16 v[0:3], v[142:145], v[166:169], v[0:3]
	s_setprio 0
	s_branch .LBB0_317

.LBB0_413:
	ds_read_b128 v[146:149], v210
	ds_read_b128 v[150:153], v210 offset:1024
	ds_read_b128 v[154:157], v210 offset:2048
	ds_read_b128 v[158:161], v210 offset:3072
	ds_read_b128 v[130:133], v210 offset:16384
	ds_read_b128 v[134:137], v210 offset:17408
	ds_read_b128 v[138:141], v210 offset:18432
	ds_read_b128 v[142:145], v210 offset:19456
	s_mov_b32 s38, m0
	s_mov_b32 m0, s30
	s_nop 0
	global_load_lds_dwordx4 v195, s[46:47]
	s_mov_b32 m0, s38
	s_nop 0
	s_mov_b32 s38, m0
	s_mov_b32 m0, s14
	s_nop 0
	global_load_lds_dwordx4 v197, s[46:47]
	s_mov_b32 m0, s38
	s_add_u32 s38, s46, 0xfffc0080
	s_addc_u32 s39, s47, -1
	s_cmp_eq_u32 s19, 12
	s_cselect_b32 s75, s27, s39
	s_cselect_b32 s74, s99, s38
	s_cselect_b32 s63, s23, s18
	s_cselect_b32 s62, s3, s8
	s_waitcnt lgkmcnt(0)
	ds_read_b128 v[162:165], v209
	ds_read_b128 v[166:169], v209 offset:1024
	ds_read_b128 v[170:173], v209 offset:2048
	ds_read_b128 v[174:177], v209 offset:3072
	ds_read_b128 v[178:181], v209 offset:4096
	ds_read_b128 v[182:185], v209 offset:5120
	ds_read_b128 v[186:189], v209 offset:6144
	ds_read_b128 v[190:193], v209 offset:7168
	s_waitcnt vmcnt(8)
	s_waitcnt lgkmcnt(0)
	s_setprio 1
	s_barrier
	v_mfma_f32_16x16x32_bf16 v[124:127], v[146:149], v[162:165], v[124:127]
	v_mfma_f32_16x16x32_bf16 v[120:123], v[154:157], v[162:165], v[120:123]
	v_mfma_f32_16x16x32_bf16 v[108:111], v[146:149], v[170:173], v[108:111]
	v_mfma_f32_16x16x32_bf16 v[104:107], v[154:157], v[170:173], v[104:107]
	v_mfma_f32_16x16x32_bf16 v[92:95], v[146:149], v[178:181], v[92:95]
	v_mfma_f32_16x16x32_bf16 v[88:91], v[154:157], v[178:181], v[88:91]
	v_mfma_f32_16x16x32_bf16 v[76:79], v[146:149], v[186:189], v[76:79]
	v_mfma_f32_16x16x32_bf16 v[72:75], v[154:157], v[186:189], v[72:75]
	v_mfma_f32_16x16x32_bf16 v[124:127], v[150:153], v[166:169], v[124:127]
	v_mfma_f32_16x16x32_bf16 v[120:123], v[158:161], v[166:169], v[120:123]
	v_mfma_f32_16x16x32_bf16 v[108:111], v[150:153], v[174:177], v[108:111]
	v_mfma_f32_16x16x32_bf16 v[104:107], v[158:161], v[174:177], v[104:107]
	v_mfma_f32_16x16x32_bf16 v[92:95], v[150:153], v[182:185], v[92:95]
	v_mfma_f32_16x16x32_bf16 v[88:91], v[158:161], v[182:185], v[88:91]
	v_mfma_f32_16x16x32_bf16 v[76:79], v[150:153], v[190:193], v[76:79]
	v_mfma_f32_16x16x32_bf16 v[72:75], v[158:161], v[190:193], v[72:75]
	s_setprio 0
	s_setprio 1
	v_mfma_f32_16x16x32_bf16 v[116:119], v[130:133], v[162:165], v[116:119]
	v_mfma_f32_16x16x32_bf16 v[112:115], v[138:141], v[162:165], v[112:115]
	v_mfma_f32_16x16x32_bf16 v[100:103], v[130:133], v[170:173], v[100:103]
	v_mfma_f32_16x16x32_bf16 v[96:99], v[138:141], v[170:173], v[96:99]
	v_mfma_f32_16x16x32_bf16 v[84:87], v[130:133], v[178:181], v[84:87]
	v_mfma_f32_16x16x32_bf16 v[80:83], v[138:141], v[178:181], v[80:83]
	v_mfma_f32_16x16x32_bf16 v[68:71], v[130:133], v[186:189], v[68:71]
	v_mfma_f32_16x16x32_bf16 v[64:67], v[138:141], v[186:189], v[64:67]
	v_mfma_f32_16x16x32_bf16 v[116:119], v[134:137], v[166:169], v[116:119]
	v_mfma_f32_16x16x32_bf16 v[112:115], v[142:145], v[166:169], v[112:115]
	v_mfma_f32_16x16x32_bf16 v[100:103], v[134:137], v[174:177], v[100:103]
	v_mfma_f32_16x16x32_bf16 v[96:99], v[142:145], v[174:177], v[96:99]
	v_mfma_f32_16x16x32_bf16 v[84:87], v[134:137], v[182:185], v[84:87]
	v_mfma_f32_16x16x32_bf16 v[80:83], v[142:145], v[182:185], v[80:83]
	v_mfma_f32_16x16x32_bf16 v[68:71], v[134:137], v[190:193], v[68:71]
	v_mfma_f32_16x16x32_bf16 v[64:67], v[142:145], v[190:193], v[64:67]
	s_setprio 0
	s_barrier
	s_mov_b32 s38, m0
	s_mov_b32 m0, s67
	s_nop 0
	global_load_lds_dwordx4 v196, s[62:63]
	s_mov_b32 m0, s38
	s_add_u32 s44, s62, 0x40000
	s_mov_b32 s38, m0
	s_mov_b32 m0, s86
	s_nop 0
	global_load_lds_dwordx4 v198, s[62:63]
	s_mov_b32 m0, s38
	s_addc_u32 s45, s63, 0
	s_mov_b32 s38, m0
	s_mov_b32 m0, s87
	s_nop 0
	global_load_lds_dwordx4 v196, s[44:45]
	s_mov_b32 m0, s38
	v_cndmask_b32_e64 v128, 0, 1, s[72:73]
	s_mov_b32 s38, m0
	s_mov_b32 m0, s88
	s_nop 0
	global_load_lds_dwordx4 v198, s[44:45]
	s_mov_b32 m0, s38
	v_cmp_ne_u32_e64 s[44:45], 1, v128
	s_mov_b32 s38, m0
	s_mov_b32 m0, s51
	s_nop 0
	global_load_lds_dwordx4 v195, s[74:75]
	s_mov_b32 m0, s38
	s_andn2_b64 vcc, exec, s[72:73]
	s_mov_b32 s38, m0
	s_mov_b32 m0, s89
	s_nop 0
	global_load_lds_dwordx4 v197, s[74:75]
	s_mov_b32 m0, s38
	ds_read_b128 v[186:189], v209 offset:16384
	ds_read_b128 v[190:193], v209 offset:17408
	ds_read_b128 v[178:181], v209 offset:18432
	ds_read_b128 v[182:185], v209 offset:19456
	ds_read_b128 v[170:173], v209 offset:20480
	ds_read_b128 v[174:177], v209 offset:21504
	ds_read_b128 v[162:165], v209 offset:22528
	ds_read_b128 v[166:169], v209 offset:23552
	s_waitcnt vmcnt(8)
	s_waitcnt lgkmcnt(0)
	s_barrier
	s_cbranch_vccnz .LBB0_415
	s_setprio 1
	v_mfma_f32_16x16x32_bf16 v[60:63], v[146:149], v[186:189], v[60:63]
	v_mfma_f32_16x16x32_bf16 v[56:59], v[154:157], v[186:189], v[56:59]
	v_mfma_f32_16x16x32_bf16 v[44:47], v[146:149], v[178:181], v[44:47]
	v_mfma_f32_16x16x32_bf16 v[40:43], v[154:157], v[178:181], v[40:43]
	v_mfma_f32_16x16x32_bf16 v[28:31], v[146:149], v[170:173], v[28:31]
	v_mfma_f32_16x16x32_bf16 v[24:27], v[154:157], v[170:173], v[24:27]
	v_mfma_f32_16x16x32_bf16 v[12:15], v[146:149], v[162:165], v[12:15]
	v_mfma_f32_16x16x32_bf16 v[8:11], v[154:157], v[162:165], v[8:11]
	v_mfma_f32_16x16x32_bf16 v[60:63], v[150:153], v[190:193], v[60:63]
	v_mfma_f32_16x16x32_bf16 v[56:59], v[158:161], v[190:193], v[56:59]
	v_mfma_f32_16x16x32_bf16 v[44:47], v[150:153], v[182:185], v[44:47]
	v_mfma_f32_16x16x32_bf16 v[40:43], v[158:161], v[182:185], v[40:43]
	v_mfma_f32_16x16x32_bf16 v[28:31], v[150:153], v[174:177], v[28:31]
	v_mfma_f32_16x16x32_bf16 v[24:27], v[158:161], v[174:177], v[24:27]
	v_mfma_f32_16x16x32_bf16 v[12:15], v[150:153], v[166:169], v[12:15]
	v_mfma_f32_16x16x32_bf16 v[8:11], v[158:161], v[166:169], v[8:11]
	s_setprio 0
	s_setprio 1
	v_mfma_f32_16x16x32_bf16 v[52:55], v[130:133], v[186:189], v[52:55]
	v_mfma_f32_16x16x32_bf16 v[48:51], v[138:141], v[186:189], v[48:51]
	v_mfma_f32_16x16x32_bf16 v[36:39], v[130:133], v[178:181], v[36:39]
	v_mfma_f32_16x16x32_bf16 v[32:35], v[138:141], v[178:181], v[32:35]
	v_mfma_f32_16x16x32_bf16 v[20:23], v[130:133], v[170:173], v[20:23]
	v_mfma_f32_16x16x32_bf16 v[16:19], v[138:141], v[170:173], v[16:19]
	v_mfma_f32_16x16x32_bf16 v[4:7], v[130:133], v[162:165], v[4:7]
	v_mfma_f32_16x16x32_bf16 v[0:3], v[138:141], v[162:165], v[0:3]
	v_mfma_f32_16x16x32_bf16 v[52:55], v[134:137], v[190:193], v[52:55]
	v_mfma_f32_16x16x32_bf16 v[48:51], v[142:145], v[190:193], v[48:51]
	v_mfma_f32_16x16x32_bf16 v[36:39], v[134:137], v[182:185], v[36:39]
	v_mfma_f32_16x16x32_bf16 v[32:35], v[142:145], v[182:185], v[32:35]
	v_mfma_f32_16x16x32_bf16 v[20:23], v[134:137], v[174:177], v[20:23]
	v_mfma_f32_16x16x32_bf16 v[16:19], v[142:145], v[174:177], v[16:19]
	v_mfma_f32_16x16x32_bf16 v[4:7], v[134:137], v[166:169], v[4:7]
	v_mfma_f32_16x16x32_bf16 v[0:3], v[142:145], v[166:169], v[0:3]
	s_setprio 0
.LBB0_415:
	s_add_u32 s76, s74, 0x80
	s_addc_u32 s77, s75, 0
	s_add_u32 s38, s62, 0x80
	s_addc_u32 s39, s63, 0
	s_barrier
	ds_read_b128 v[146:149], v210 offset:32768
	ds_read_b128 v[150:153], v210 offset:33792
	ds_read_b128 v[154:157], v210 offset:34816
	ds_read_b128 v[158:161], v210 offset:35840
	ds_read_b128 v[130:133], v210 offset:49152
	ds_read_b128 v[134:137], v210 offset:50176
	ds_read_b128 v[138:141], v210 offset:51200
	ds_read_b128 v[142:145], v210 offset:52224
	s_add_u32 s74, s74, 0x40000
	s_addc_u32 s75, s75, 0
	s_mov_b32 vcc_lo, m0
	s_mov_b32 m0, s92
	s_nop 0
	global_load_lds_dwordx4 v195, s[74:75]
	s_mov_b32 m0, vcc_lo
	s_nop 0
	s_mov_b32 vcc_lo, m0
	s_mov_b32 m0, s93
	s_nop 0
	global_load_lds_dwordx4 v197, s[74:75]
	s_mov_b32 m0, vcc_lo
	s_waitcnt lgkmcnt(0)
	ds_read_b128 v[162:165], v209 offset:32768
	ds_read_b128 v[166:169], v209 offset:33792
	ds_read_b128 v[170:173], v209 offset:34816
	ds_read_b128 v[174:177], v209 offset:35840
	ds_read_b128 v[178:181], v209 offset:36864
	ds_read_b128 v[182:185], v209 offset:37888
	ds_read_b128 v[186:189], v209 offset:38912
	ds_read_b128 v[190:193], v209 offset:39936
	s_waitcnt vmcnt(8)
	s_waitcnt lgkmcnt(0)
	s_setprio 1
	s_barrier
	v_mfma_f32_16x16x32_bf16 v[124:127], v[146:149], v[162:165], v[124:127]
	v_mfma_f32_16x16x32_bf16 v[120:123], v[154:157], v[162:165], v[120:123]
	v_mfma_f32_16x16x32_bf16 v[108:111], v[146:149], v[170:173], v[108:111]
	v_mfma_f32_16x16x32_bf16 v[104:107], v[154:157], v[170:173], v[104:107]
	v_mfma_f32_16x16x32_bf16 v[92:95], v[146:149], v[178:181], v[92:95]
	v_mfma_f32_16x16x32_bf16 v[88:91], v[154:157], v[178:181], v[88:91]
	v_mfma_f32_16x16x32_bf16 v[76:79], v[146:149], v[186:189], v[76:79]
	v_mfma_f32_16x16x32_bf16 v[72:75], v[154:157], v[186:189], v[72:75]
	v_mfma_f32_16x16x32_bf16 v[124:127], v[150:153], v[166:169], v[124:127]
	v_mfma_f32_16x16x32_bf16 v[120:123], v[158:161], v[166:169], v[120:123]
	v_mfma_f32_16x16x32_bf16 v[108:111], v[150:153], v[174:177], v[108:111]
	v_mfma_f32_16x16x32_bf16 v[104:107], v[158:161], v[174:177], v[104:107]
	v_mfma_f32_16x16x32_bf16 v[92:95], v[150:153], v[182:185], v[92:95]
	v_mfma_f32_16x16x32_bf16 v[88:91], v[158:161], v[182:185], v[88:91]
	v_mfma_f32_16x16x32_bf16 v[76:79], v[150:153], v[190:193], v[76:79]
	v_mfma_f32_16x16x32_bf16 v[72:75], v[158:161], v[190:193], v[72:75]
	s_setprio 0
	s_setprio 1
	v_mfma_f32_16x16x32_bf16 v[116:119], v[130:133], v[162:165], v[116:119]
	v_mfma_f32_16x16x32_bf16 v[112:115], v[138:141], v[162:165], v[112:115]
	v_mfma_f32_16x16x32_bf16 v[100:103], v[130:133], v[170:173], v[100:103]
	v_mfma_f32_16x16x32_bf16 v[96:99], v[138:141], v[170:173], v[96:99]
	v_mfma_f32_16x16x32_bf16 v[84:87], v[130:133], v[178:181], v[84:87]
	v_mfma_f32_16x16x32_bf16 v[80:83], v[138:141], v[178:181], v[80:83]
	v_mfma_f32_16x16x32_bf16 v[68:71], v[130:133], v[186:189], v[68:71]
	v_mfma_f32_16x16x32_bf16 v[64:67], v[138:141], v[186:189], v[64:67]
	v_mfma_f32_16x16x32_bf16 v[116:119], v[134:137], v[166:169], v[116:119]
	v_mfma_f32_16x16x32_bf16 v[112:115], v[142:145], v[166:169], v[112:115]
	v_mfma_f32_16x16x32_bf16 v[100:103], v[134:137], v[174:177], v[100:103]
	v_mfma_f32_16x16x32_bf16 v[96:99], v[142:145], v[174:177], v[96:99]
	v_mfma_f32_16x16x32_bf16 v[84:87], v[134:137], v[182:185], v[84:87]
	v_mfma_f32_16x16x32_bf16 v[80:83], v[142:145], v[182:185], v[80:83]
	v_mfma_f32_16x16x32_bf16 v[68:71], v[134:137], v[190:193], v[68:71]
	v_mfma_f32_16x16x32_bf16 v[64:67], v[142:145], v[190:193], v[64:67]
	s_setprio 0
	s_barrier
	s_mov_b32 s74, m0
	s_mov_b32 m0, s95
	s_nop 0
	global_load_lds_dwordx4 v196, s[38:39]
	s_mov_b32 m0, s74
	s_nop 0
	s_mov_b32 s74, m0
	s_mov_b32 m0, s96
	s_nop 0
	global_load_lds_dwordx4 v198, s[38:39]
	s_mov_b32 m0, s74
	s_add_u32 s38, s62, 0x40080
	s_addc_u32 s39, s63, 0
	s_mov_b32 s62, m0
	s_mov_b32 m0, s65
	s_nop 0
	global_load_lds_dwordx4 v196, s[38:39]
	s_mov_b32 m0, s62
	s_and_b64 vcc, exec, s[44:45]
	s_mov_b32 s62, m0
	s_mov_b32 m0, s50
	s_nop 0
	global_load_lds_dwordx4 v198, s[38:39]
	s_mov_b32 m0, s62
	s_mov_b32 s38, m0
	s_mov_b32 m0, s97
	s_nop 0
	global_load_lds_dwordx4 v195, s[76:77]
	s_mov_b32 m0, s38
	s_nop 0
	s_mov_b32 s38, m0
	s_mov_b32 m0, s9
	s_nop 0
	global_load_lds_dwordx4 v197, s[76:77]
	s_mov_b32 m0, s38
	ds_read_b128 v[186:189], v209 offset:49152
	ds_read_b128 v[190:193], v209 offset:50176
	ds_read_b128 v[178:181], v209 offset:51200
	ds_read_b128 v[182:185], v209 offset:52224
	ds_read_b128 v[170:173], v209 offset:53248
	ds_read_b128 v[174:177], v209 offset:54272
	ds_read_b128 v[162:165], v209 offset:55296
	ds_read_b128 v[166:169], v209 offset:56320
	s_waitcnt vmcnt(8)
	s_waitcnt lgkmcnt(0)
	s_barrier
	s_cbranch_vccnz .LBB0_412
	s_setprio 1
	v_mfma_f32_16x16x32_bf16 v[60:63], v[146:149], v[186:189], v[60:63]
	v_mfma_f32_16x16x32_bf16 v[56:59], v[154:157], v[186:189], v[56:59]
	v_mfma_f32_16x16x32_bf16 v[44:47], v[146:149], v[178:181], v[44:47]
	v_mfma_f32_16x16x32_bf16 v[40:43], v[154:157], v[178:181], v[40:43]
	v_mfma_f32_16x16x32_bf16 v[28:31], v[146:149], v[170:173], v[28:31]
	v_mfma_f32_16x16x32_bf16 v[24:27], v[154:157], v[170:173], v[24:27]
	v_mfma_f32_16x16x32_bf16 v[12:15], v[146:149], v[162:165], v[12:15]
	v_mfma_f32_16x16x32_bf16 v[8:11], v[154:157], v[162:165], v[8:11]
	v_mfma_f32_16x16x32_bf16 v[60:63], v[150:153], v[190:193], v[60:63]
	v_mfma_f32_16x16x32_bf16 v[56:59], v[158:161], v[190:193], v[56:59]
	v_mfma_f32_16x16x32_bf16 v[44:47], v[150:153], v[182:185], v[44:47]
	v_mfma_f32_16x16x32_bf16 v[40:43], v[158:161], v[182:185], v[40:43]
	v_mfma_f32_16x16x32_bf16 v[28:31], v[150:153], v[174:177], v[28:31]
	v_mfma_f32_16x16x32_bf16 v[24:27], v[158:161], v[174:177], v[24:27]
	v_mfma_f32_16x16x32_bf16 v[12:15], v[150:153], v[166:169], v[12:15]
	v_mfma_f32_16x16x32_bf16 v[8:11], v[158:161], v[166:169], v[8:11]
	s_setprio 0
	s_setprio 1
	v_mfma_f32_16x16x32_bf16 v[52:55], v[130:133], v[186:189], v[52:55]
	v_mfma_f32_16x16x32_bf16 v[48:51], v[138:141], v[186:189], v[48:51]
	v_mfma_f32_16x16x32_bf16 v[36:39], v[130:133], v[178:181], v[36:39]
	v_mfma_f32_16x16x32_bf16 v[32:35], v[138:141], v[178:181], v[32:35]
	v_mfma_f32_16x16x32_bf16 v[20:23], v[130:133], v[170:173], v[20:23]
	v_mfma_f32_16x16x32_bf16 v[16:19], v[138:141], v[170:173], v[16:19]
	v_mfma_f32_16x16x32_bf16 v[4:7], v[130:133], v[162:165], v[4:7]
	v_mfma_f32_16x16x32_bf16 v[0:3], v[138:141], v[162:165], v[0:3]
	v_mfma_f32_16x16x32_bf16 v[52:55], v[134:137], v[190:193], v[52:55]
	v_mfma_f32_16x16x32_bf16 v[48:51], v[142:145], v[190:193], v[48:51]
	v_mfma_f32_16x16x32_bf16 v[36:39], v[134:137], v[182:185], v[36:39]
	v_mfma_f32_16x16x32_bf16 v[32:35], v[142:145], v[182:185], v[32:35]
	v_mfma_f32_16x16x32_bf16 v[20:23], v[134:137], v[174:177], v[20:23]
	v_mfma_f32_16x16x32_bf16 v[16:19], v[142:145], v[174:177], v[16:19]
	v_mfma_f32_16x16x32_bf16 v[4:7], v[134:137], v[166:169], v[4:7]
	v_mfma_f32_16x16x32_bf16 v[0:3], v[142:145], v[166:169], v[0:3]
	s_setprio 0
	s_branch .LBB0_412
